# stagger variant: waves 0-3 rendezvous right after their QK LDS reads, waves 4-7 at the tile end (FoX+MLA in-loop tiles)
# speedup vs baseline: 1.0041x; 1.0041x over previous
; __device__ __forceinline__ unsigned cvt_pk_bf16(float lo, float hi) { f32x2 v = {lo, hi}; bf16x2_t b = __builtin_convertvector(v, bf16x2_t); return __builtin_bit_cast(unsigned, b); }
; template <int TY> __device__ __forceinline__ void attn_unit(LAS unsigned char* lds, const AttnArgs& a, int b, int h, int qt, int wave_s) {
;     ...
; #pragma unroll
;         for (int qb = 0; qb < 2; ++qb) {
; #pragma unroll
;             for (int kb = 0; kb < 4; ++kb)
; #pragma unroll
;                 for (int r = 0; r < 4; ++r) s[qb][kb][r] = __builtin_amdgcn_exp2f(s[qb][kb][r]);
; #pragma unroll
;             for (int G = 0; G < 2; ++G) {
;                 u32x4 w; w.x = cvt_pk_bf16(s[qb][2 * G][0], s[qb][2 * G][1]); w.y = cvt_pk_bf16(s[qb][2 * G][2], s[qb][2 * G][3]);
;                 w.z = cvt_pk_bf16(s[qb][2 * G + 1][0], s[qb][2 * G + 1][1]); w.w = cvt_pk_bf16(s[qb][2 * G + 1][2], s[qb][2 * G + 1][3]);
;                 pf[qb][G] = __builtin_bit_cast(bf16x8, w);
;             }
;         }
.LBB0_708:
	v_exp_f32_e32 v130, v130
	v_exp_f32_e32 v131, v131
	v_exp_f32_e32 v132, v132
	v_exp_f32_e32 v133, v133
	v_exp_f32_e32 v146, v146
	v_exp_f32_e32 v147, v147
	v_exp_f32_e32 v148, v148
	v_exp_f32_e32 v149, v149
	v_exp_f32_e32 v163, v14
	v_exp_f32_e32 v164, v15
	v_cvt_pk_bf16_f32 v130, v130, v131
	v_exp_f32_e32 v10, v10
	v_exp_f32_e32 v11, v11
	v_exp_f32_e32 v12, v12
	v_exp_f32_e32 v13, v13
	v_exp_f32_e32 v14, v106
	v_exp_f32_e32 v15, v107
	v_exp_f32_e32 v106, v108
	v_exp_f32_e32 v107, v109
	v_exp_f32_e32 v108, v126
	v_exp_f32_e32 v109, v127
	v_exp_f32_e32 v126, v128
	v_exp_f32_e32 v127, v129
	v_exp_f32_e32 v128, v134
	v_exp_f32_e32 v131, v136
	v_exp_f32_e32 v134, v137
	v_exp_f32_e32 v154, v154
	v_exp_f32_e32 v155, v155
	v_exp_f32_e32 v156, v156
	v_exp_f32_e32 v157, v157
	v_exp_f32_e32 v129, v135
	v_cvt_pk_bf16_f32 v10, v10, v11
	v_cvt_pk_bf16_f32 v11, v12, v13
	v_cvt_pk_bf16_f32 v12, v14, v15
	v_cvt_pk_bf16_f32 v13, v106, v107
	v_cvt_pk_bf16_f32 v106, v108, v109
	v_cvt_pk_bf16_f32 v107, v126, v127
	v_cvt_pk_bf16_f32 v109, v131, v134
	v_cvt_pk_bf16_f32 v131, v132, v133
	v_cvt_pk_bf16_f32 v132, v146, v147
	v_cvt_pk_bf16_f32 v133, v148, v149
	v_exp_f32_e32 v126, v16
	v_exp_f32_e32 v17, v17
	s_bitcmp1_b32 s41, 8
	s_branch .Lml_h0p2_end
	s_cmp_ge_u32 s22, s18
	s_cbranch_scc1 .Lml_h0p2_bar
	s_waitcnt vmcnt(5)
	ds_write_b128 v208, v[66:69] offset:22784
	s_and_saveexec_b64 s[100:101], s[4:5]
	s_cbranch_execz .Lml_h0p2_w
	v_add_u32_e32 v232, 0, v209
	s_waitcnt vmcnt(3)
	ds_write_b128 v232, v[74:77] offset:24832

; template <int TY> __device__ __forceinline__ void attn_unit(LAS unsigned char* lds, const AttnArgs& a, int b, int h, int qt, int wave_s) {
;     ...
; #pragma unroll
;         for (int G = 0; G < 2; ++G) {
;             lacc[0] = __builtin_amdgcn_mfma_f32_16x16x32_bf16(ones, pf[0][G], lacc[0], 0, 0, 0);
;             lacc[1] = __builtin_amdgcn_mfma_f32_16x16x32_bf16(ones, pf[1][G], lacc[1], 0, 0, 0);
;         }
; #pragma unroll
;         for (int db = 0; db < 4; ++db)
; #pragma unroll
;             for (int G = 0; G < 2; ++G) {
;                 o[0][db] = __builtin_amdgcn_mfma_f32_16x16x32_bf16(vf[db][G], pf[0][G], o[0][db], 0, 0, 0);
;                 o[1][db] = __builtin_amdgcn_mfma_f32_16x16x32_bf16(vf[db][G], pf[1][G], o[1][db], 0, 0, 0);
;             }
.Lml_h0p2_end:
	v_mfma_f32_16x16x32_bf16 v[6:9], v[54:57], v[10:13], v[6:9]
	v_cvt_pk_bf16_f32 v108, v128, v129
	v_cvt_pk_bf16_f32 v14, v154, v155
	v_cvt_pk_bf16_f32 v15, v156, v157
	s_waitcnt lgkmcnt(13)
	v_mfma_f32_16x16x32_bf16 v[102:105], v[122:125], v[130:133], v[102:105]
	v_cvt_pk_bf16_f32 v16, v163, v164
	v_cvt_pk_bf16_f32 v17, v126, v17
	v_mfma_f32_16x16x32_bf16 v[34:37], v[122:125], v[10:13], v[34:37]
	s_waitcnt lgkmcnt(10)
	v_mfma_f32_16x16x32_bf16 v[98:101], v[110:113], v[130:133], v[98:101]
	v_mfma_f32_16x16x32_bf16 v[30:33], v[110:113], v[10:13], v[30:33]
	s_waitcnt lgkmcnt(6)
	v_mfma_f32_16x16x32_bf16 v[94:97], v[142:145], v[130:133], v[94:97]
	v_mfma_f32_16x16x32_bf16 v[26:29], v[142:145], v[10:13], v[26:29]
	s_waitcnt lgkmcnt(2)
	v_mfma_f32_16x16x32_bf16 v[90:93], v[150:153], v[130:133], v[90:93]
	v_mfma_f32_16x16x32_bf16 v[10:13], v[150:153], v[10:13], v[22:25]
	v_mfma_f32_16x16x32_bf16 v[2:5], v[54:57], v[130:133], v[2:5]
	v_mfma_f32_16x16x32_bf16 v[6:9], v[54:57], v[106:109], v[6:9]
	v_mfma_f32_16x16x32_bf16 v[102:105], v[118:121], v[14:17], v[102:105]
	v_mfma_f32_16x16x32_bf16 v[34:37], v[118:121], v[106:109], v[34:37]
	v_mfma_f32_16x16x32_bf16 v[98:101], v[114:117], v[14:17], v[98:101]
	v_mfma_f32_16x16x32_bf16 v[30:33], v[114:117], v[106:109], v[30:33]
	v_mfma_f32_16x16x32_bf16 v[94:97], v[138:141], v[14:17], v[94:97]
	v_mfma_f32_16x16x32_bf16 v[26:29], v[138:141], v[106:109], v[26:29]
	s_waitcnt lgkmcnt(0)
	v_mfma_f32_16x16x32_bf16 v[90:93], v[158:161], v[14:17], v[90:93]
	v_mfma_f32_16x16x32_bf16 v[22:25], v[158:161], v[106:109], v[10:13]
	v_mfma_f32_16x16x32_bf16 v[2:5], v[54:57], v[14:17], v[2:5]
	s_bitcmp1_b32 s41, 8
	s_cbranch_scc0 .LBB0_714

; __device__ __forceinline__ unsigned cvt_pk_bf16(float lo, float hi) { f32x2 v = {lo, hi}; bf16x2_t b = __builtin_convertvector(v, bf16x2_t); return __builtin_bit_cast(unsigned, b); }
; template <int TY> __device__ __forceinline__ void attn_unit(LAS unsigned char* lds, const AttnArgs& a, int b, int h, int qt, int wave_s) {
;     ...
; #pragma unroll
;         for (int qb = 0; qb < 2; ++qb) {
; #pragma unroll
;             for (int kb = 0; kb < 4; ++kb)
; #pragma unroll
;                 for (int r = 0; r < 4; ++r) s[qb][kb][r] = __builtin_amdgcn_exp2f(s[qb][kb][r]);
; #pragma unroll
;             for (int G = 0; G < 2; ++G) {
;                 u32x4 w; w.x = cvt_pk_bf16(s[qb][2 * G][0], s[qb][2 * G][1]); w.y = cvt_pk_bf16(s[qb][2 * G][2], s[qb][2 * G][3]);
;                 w.z = cvt_pk_bf16(s[qb][2 * G + 1][0], s[qb][2 * G + 1][1]); w.w = cvt_pk_bf16(s[qb][2 * G + 1][2], s[qb][2 * G + 1][3]);
;                 pf[qb][G] = __builtin_bit_cast(bf16x8, w);
;             }
;         }
.LBB0_723:
	v_exp_f32_e32 v130, v130
	v_exp_f32_e32 v131, v131
	v_exp_f32_e32 v132, v132
	v_exp_f32_e32 v133, v133
	v_exp_f32_e32 v146, v146
	v_exp_f32_e32 v147, v147
	v_exp_f32_e32 v148, v148
	v_exp_f32_e32 v149, v149
	v_exp_f32_e32 v163, v14
	v_exp_f32_e32 v164, v15
	v_cvt_pk_bf16_f32 v130, v130, v131
	v_exp_f32_e32 v10, v10
	v_exp_f32_e32 v11, v11
	v_exp_f32_e32 v12, v12
	v_exp_f32_e32 v13, v13
	v_exp_f32_e32 v14, v106
	v_exp_f32_e32 v15, v107
	v_exp_f32_e32 v106, v108
	v_exp_f32_e32 v107, v109
	v_exp_f32_e32 v108, v126
	v_exp_f32_e32 v109, v127
	v_exp_f32_e32 v126, v128
	v_exp_f32_e32 v127, v129
	v_exp_f32_e32 v128, v134
	v_exp_f32_e32 v131, v136
	v_exp_f32_e32 v134, v137
	v_exp_f32_e32 v154, v154
	v_exp_f32_e32 v155, v155
	v_exp_f32_e32 v156, v156
	v_exp_f32_e32 v157, v157
	v_exp_f32_e32 v129, v135
	v_cvt_pk_bf16_f32 v10, v10, v11
	v_cvt_pk_bf16_f32 v11, v12, v13
	v_cvt_pk_bf16_f32 v12, v14, v15
	v_cvt_pk_bf16_f32 v13, v106, v107
	v_cvt_pk_bf16_f32 v106, v108, v109
	v_cvt_pk_bf16_f32 v107, v126, v127
	v_cvt_pk_bf16_f32 v109, v131, v134
	v_cvt_pk_bf16_f32 v131, v132, v133
	v_cvt_pk_bf16_f32 v132, v146, v147
	v_cvt_pk_bf16_f32 v133, v148, v149
	v_exp_f32_e32 v126, v16
	v_exp_f32_e32 v17, v17
	s_bitcmp1_b32 s41, 8
	s_branch .Lml_h1p2_end
	s_add_i32 s99, s20, -2
	s_cmp_ge_u32 s99, s18
	s_cbranch_scc1 .Lml_h1p2_bar
	s_waitcnt vmcnt(5)
	ds_write_b128 v208, v[78:81]
	s_and_saveexec_b64 s[100:101], s[4:5]
	s_cbranch_execz .Lml_h1p2_w
	v_add_u32_e32 v232, 0, v209
	s_waitcnt vmcnt(3)
	ds_write_b128 v232, v[86:89] offset:2048

; __device__ __forceinline__ unsigned cvt_pk_bf16(float lo, float hi) { f32x2 v = {lo, hi}; bf16x2_t b = __builtin_convertvector(v, bf16x2_t); return __builtin_bit_cast(unsigned, b); }
; template <int TY> __device__ __forceinline__ void attn_unit(LAS unsigned char* lds, const AttnArgs& a, int b, int h, int qt, int wave_s) {
;     ...
; #pragma unroll
;         for (int qb = 0; qb < 2; ++qb) {
; #pragma unroll
;             for (int kb = 0; kb < 4; ++kb)
; #pragma unroll
;                 for (int r = 0; r < 4; ++r) s[qb][kb][r] = __builtin_amdgcn_exp2f(s[qb][kb][r]);
; #pragma unroll
;             for (int G = 0; G < 2; ++G) {
;                 u32x4 w; w.x = cvt_pk_bf16(s[qb][2 * G][0], s[qb][2 * G][1]); w.y = cvt_pk_bf16(s[qb][2 * G][2], s[qb][2 * G][3]);
;                 w.z = cvt_pk_bf16(s[qb][2 * G + 1][0], s[qb][2 * G + 1][1]); w.w = cvt_pk_bf16(s[qb][2 * G + 1][2], s[qb][2 * G + 1][3]);
;                 pf[qb][G] = __builtin_bit_cast(bf16x8, w);
;             }
;         }
.LBB0_771:
	v_exp_f32_e32 v114, v114
	v_exp_f32_e32 v115, v115
	v_exp_f32_e32 v116, v116
	v_exp_f32_e32 v117, v117
	v_exp_f32_e32 v126, v126
	v_exp_f32_e32 v127, v127
	v_exp_f32_e32 v128, v128
	v_exp_f32_e32 v129, v129
	v_cvt_pk_bf16_f32 v114, v114, v115
	v_exp_f32_e32 v18, v18
	v_exp_f32_e32 v1, v1
	v_exp_f32_e32 v20, v20
	v_exp_f32_e32 v21, v21
	v_exp_f32_e32 v115, v118
	v_exp_f32_e32 v142, v119
	v_exp_f32_e32 v143, v120
	v_exp_f32_e32 v121, v121
	v_exp_f32_e32 v130, v130
	v_exp_f32_e32 v131, v131
	v_exp_f32_e32 v132, v132
	v_exp_f32_e32 v133, v133
	v_exp_f32_e32 v140, v140
	v_exp_f32_e32 v141, v141
	v_exp_f32_e32 v122, v122
	v_exp_f32_e32 v123, v123
	v_exp_f32_e32 v124, v124
	v_exp_f32_e32 v125, v125
	v_exp_f32_e32 v136, v136
	v_exp_f32_e32 v137, v137
	v_exp_f32_e32 v138, v138
	v_exp_f32_e32 v139, v139
	v_cvt_pk_bf16_f32 v118, v18, v1
	v_cvt_pk_bf16_f32 v119, v20, v21
	v_cvt_pk_bf16_f32 v120, v115, v142
	v_cvt_pk_bf16_f32 v121, v143, v121
	v_cvt_pk_bf16_f32 v115, v116, v117
	v_cvt_pk_bf16_f32 v116, v126, v127
	v_cvt_pk_bf16_f32 v117, v128, v129
	v_exp_f32_e32 v1, v134
	v_exp_f32_e32 v18, v135
	s_bitcmp1_b32 s41, 8
	s_branch .Lfx_h0p2_end
	s_cmp_ge_u32 s24, s20
	s_cbranch_scc1 .Lfx_h0p2_bar
	s_waitcnt vmcnt(5)
	ds_write_b128 v182, v[62:65] offset:18688
	s_waitcnt vmcnt(4)
	ds_write_b128 v183, v[66:69] offset:26880
	s_and_saveexec_b64 s[100:101], s[4:5]
	s_cbranch_execz .Lfx_h0p2_w
	s_waitcnt vmcnt(3)
	ds_write_b32 v184, v185 offset:37120

; template <int TY> __device__ __forceinline__ void attn_unit(LAS unsigned char* lds, const AttnArgs& a, int b, int h, int qt, int wave_s) {
;     ...
; #pragma unroll
;         for (int G = 0; G < 2; ++G) {
;             lacc[0] = __builtin_amdgcn_mfma_f32_16x16x32_bf16(ones, pf[0][G], lacc[0], 0, 0, 0);
;             lacc[1] = __builtin_amdgcn_mfma_f32_16x16x32_bf16(ones, pf[1][G], lacc[1], 0, 0, 0);
;         }
; #pragma unroll
;         for (int db = 0; db < 4; ++db)
; #pragma unroll
;             for (int G = 0; G < 2; ++G) {
;                 o[0][db] = __builtin_amdgcn_mfma_f32_16x16x32_bf16(vf[db][G], pf[0][G], o[0][db], 0, 0, 0);
;                 o[1][db] = __builtin_amdgcn_mfma_f32_16x16x32_bf16(vf[db][G], pf[1][G], o[1][db], 0, 0, 0);
;             }
.Lfx_h0p2_end:
	v_mfma_f32_16x16x32_bf16 v[82:85], v[10:13], v[114:117], v[82:85]
	v_cvt_pk_bf16_f32 v122, v122, v123
	v_cvt_pk_bf16_f32 v123, v124, v125
	v_cvt_pk_bf16_f32 v124, v136, v137
	v_mfma_f32_16x16x32_bf16 v[10:13], v[10:13], v[118:121], v[30:33]
	v_cvt_pk_bf16_f32 v125, v138, v139
	v_cvt_pk_bf16_f32 v126, v130, v131
	v_cvt_pk_bf16_f32 v127, v132, v133
	v_cvt_pk_bf16_f32 v128, v140, v141
	v_cvt_pk_bf16_f32 v129, v1, v18
	v_mfma_f32_16x16x32_bf16 v[30:33], v[14:17], v[122:125], v[10:13]
	s_nop 0
	v_mfma_f32_16x16x32_bf16 v[82:85], v[14:17], v[126:129], v[82:85]
	v_mfma_f32_16x16x32_bf16 v[10:13], v[102:105], v[114:117], v[78:81]
	v_mfma_f32_16x16x32_bf16 v[14:17], v[102:105], v[118:121], v[26:29]
	v_mfma_f32_16x16x32_bf16 v[6:9], v[54:57], v[118:121], v[6:9]
	v_mfma_f32_16x16x32_bf16 v[86:89], v[94:97], v[114:117], v[86:89]
	v_mfma_f32_16x16x32_bf16 v[34:37], v[94:97], v[118:121], v[34:37]
	v_mfma_f32_16x16x32_bf16 v[78:81], v[98:101], v[126:129], v[10:13]
	v_mfma_f32_16x16x32_bf16 v[26:29], v[98:101], v[122:125], v[14:17]
	v_mfma_f32_16x16x32_bf16 v[10:13], v[106:109], v[114:117], v[58:61]
	v_mfma_f32_16x16x32_bf16 v[14:17], v[106:109], v[118:121], v[22:25]
	v_mfma_f32_16x16x32_bf16 v[2:5], v[54:57], v[114:117], v[2:5]
	v_mfma_f32_16x16x32_bf16 v[6:9], v[54:57], v[122:125], v[6:9]
	v_mfma_f32_16x16x32_bf16 v[86:89], v[90:93], v[126:129], v[86:89]
	v_mfma_f32_16x16x32_bf16 v[34:37], v[90:93], v[122:125], v[34:37]
	v_mfma_f32_16x16x32_bf16 v[58:61], v[110:113], v[126:129], v[10:13]
	v_mfma_f32_16x16x32_bf16 v[22:25], v[110:113], v[122:125], v[14:17]
	v_mfma_f32_16x16x32_bf16 v[2:5], v[54:57], v[126:129], v[2:5]
	s_bitcmp1_b32 s41, 8
	s_cbranch_scc0 .LBB0_777

; __device__ __forceinline__ unsigned cvt_pk_bf16(float lo, float hi) { f32x2 v = {lo, hi}; bf16x2_t b = __builtin_convertvector(v, bf16x2_t); return __builtin_bit_cast(unsigned, b); }
; template <int TY> __device__ __forceinline__ void attn_unit(LAS unsigned char* lds, const AttnArgs& a, int b, int h, int qt, int wave_s) {
;     ...
; #pragma unroll
;         for (int qb = 0; qb < 2; ++qb) {
; #pragma unroll
;             for (int kb = 0; kb < 4; ++kb)
; #pragma unroll
;                 for (int r = 0; r < 4; ++r) s[qb][kb][r] = __builtin_amdgcn_exp2f(s[qb][kb][r]);
; #pragma unroll
;             for (int G = 0; G < 2; ++G) {
;                 u32x4 w; w.x = cvt_pk_bf16(s[qb][2 * G][0], s[qb][2 * G][1]); w.y = cvt_pk_bf16(s[qb][2 * G][2], s[qb][2 * G][3]);
;                 w.z = cvt_pk_bf16(s[qb][2 * G + 1][0], s[qb][2 * G + 1][1]); w.w = cvt_pk_bf16(s[qb][2 * G + 1][2], s[qb][2 * G + 1][3]);
;                 pf[qb][G] = __builtin_bit_cast(bf16x8, w);
;             }
;         }
.LBB0_786:
	v_exp_f32_e32 v114, v114
	v_exp_f32_e32 v115, v115
	v_exp_f32_e32 v116, v116
	v_exp_f32_e32 v117, v117
	v_exp_f32_e32 v126, v126
	v_exp_f32_e32 v127, v127
	v_exp_f32_e32 v128, v128
	v_exp_f32_e32 v129, v129
	v_cvt_pk_bf16_f32 v114, v114, v115
	v_exp_f32_e32 v18, v18
	v_exp_f32_e32 v1, v1
	v_exp_f32_e32 v20, v20
	v_exp_f32_e32 v21, v21
	v_exp_f32_e32 v115, v118
	v_exp_f32_e32 v142, v119
	v_exp_f32_e32 v143, v120
	v_exp_f32_e32 v121, v121
	v_exp_f32_e32 v130, v130
	v_exp_f32_e32 v131, v131
	v_exp_f32_e32 v132, v132
	v_exp_f32_e32 v133, v133
	v_exp_f32_e32 v140, v140
	v_exp_f32_e32 v141, v141
	v_exp_f32_e32 v122, v122
	v_exp_f32_e32 v123, v123
	v_exp_f32_e32 v124, v124
	v_exp_f32_e32 v125, v125
	v_exp_f32_e32 v136, v136
	v_exp_f32_e32 v137, v137
	v_exp_f32_e32 v138, v138
	v_exp_f32_e32 v139, v139
	v_cvt_pk_bf16_f32 v118, v18, v1
	v_cvt_pk_bf16_f32 v119, v20, v21
	v_cvt_pk_bf16_f32 v120, v115, v142
	v_cvt_pk_bf16_f32 v121, v143, v121
	v_cvt_pk_bf16_f32 v115, v116, v117
	v_cvt_pk_bf16_f32 v116, v126, v127
	v_cvt_pk_bf16_f32 v117, v128, v129
	v_exp_f32_e32 v1, v134
	v_exp_f32_e32 v18, v135
	s_bitcmp1_b32 s41, 8
	s_branch .Lfx_h1p2_end
	s_add_i32 s100, s22, -2
	s_cmp_ge_u32 s100, s20
	s_cbranch_scc1 .Lfx_h1p2_bar
	s_waitcnt vmcnt(5)
	ds_write_b128 v182, v[70:73]
	s_waitcnt vmcnt(4)
	ds_write_b128 v183, v[74:77] offset:8192
	s_and_saveexec_b64 s[100:101], s[4:5]
	s_cbranch_execz .Lfx_h1p2_w
	s_waitcnt vmcnt(3)
	ds_write_b32 v184, v189 offset:18432
